# baseline (speedup 1.0000x reference)
; template <bool BOUNDARY, bool Q0, bool Q1>
; __device__ __forceinline__ void attn_tile(const bf16* Ks, const bf16* Vt, const bf16x8 (&Qf)[2][2], const uint32_t (&vm)[2],
;                                           float (&m)[2], float (&l)[2], f32x4 (&O)[4][2], int fr, int fq) {
;     ...
; #pragma unroll
;   for (int kt = 0; kt < 4; ++kt) {
;     S[kt][0] = f32x4{0.f, 0.f, 0.f, 0.f};
;     S[kt][1] = f32x4{0.f, 0.f, 0.f, 0.f};
; #pragma unroll
;     for (int ks = 0; ks < 2; ++ks) {
;       const bf16x8 kf = *(const bf16x8*)(Ks + (16 * kt + fr) * KS_LD + 32 * ks + 8 * fq);
;       if (Q0) S[kt][0] = __builtin_amdgcn_mfma_f32_16x16x32_bf16(kf, Qf[0][ks], S[kt][0], 0, 0, 0);
;       if (Q1) S[kt][1] = __builtin_amdgcn_mfma_f32_16x16x32_bf16(kf, Qf[1][ks], S[kt][1], 0, 0, 0);
;     }
;   }
; #pragma unroll
;   for (int qt = 0; qt < 2; ++qt) {
;     if ((qt == 0 && !Q0) || (qt == 1 && !Q1)) continue;
;     float mx, mxu;
;     if (BOUNDARY) {
;       mx = m[qt];
; #pragma unroll
;       for (int kt = 0; kt < 4; ++kt)
; #pragma unroll
;         for (int j = 0; j < 4; ++j) {
;           const float s2 = S[kt][qt][j];
;           if ((vm[qt] >> (kt * 4 + j)) & 1u) mx = fmaxf(mx, s2);
;         }
;       mx = fmaxf(mx, __shfl_xor(mx, 16));
;       mx = fmaxf(mx, __shfl_xor(mx, 32));
;       mxu = mx;
;     } else {
;       float rm = -3.0e38f;
; #pragma unroll
;       for (int kt = 0; kt < 4; ++kt)
; #pragma unroll
;         for (int j = 0; j < 4; ++j) {
;           rm = fmaxf(rm, S[kt][qt][j]);
;         }
;       rm = fmaxf(rm, __shfl_xor(rm, 16));
;       rm = fmaxf(rm, __shfl_xor(rm, 32));
;       const bool rv = vm[qt] != 0u;
;       mx = rv ? fmaxf(m[qt], rm) : m[qt];
;       mxu = rv ? mx : 3.0e38f;
;     }
;     const float alpha = __builtin_amdgcn_exp2f(m[qt] - mx);
;     m[qt] = mx;
;     float ls = 0.f;
; #pragma unroll
;     for (int kt = 0; kt < 4; ++kt)
; #pragma unroll
;       for (int j = 0; j < 4; ++j) {
;         float pv;
;         if (BOUNDARY) pv = ((vm[qt] >> (kt * 4 + j)) & 1u) ? __builtin_amdgcn_exp2f(S[kt][qt][j] - mxu) : 0.f;
;         else pv = __builtin_amdgcn_exp2f(S[kt][qt][j] - mxu);
;         S[kt][qt][j] = pv;
;         ls += pv;
;       }
;     l[qt] = l[qt] * alpha + ls;
; #pragma unroll
;     for (int dt = 0; dt < 4; ++dt) {
;       O[dt][qt][0] *= alpha; O[dt][qt][1] *= alpha; O[dt][qt][2] *= alpha; O[dt][qt][3] *= alpha;
;     }
;   }
.LBB0_665:
	s_andn2_b64 vcc, exec, s[8:9]
	s_cbranch_vccnz .LBB0_675
	v_add_u32_e32 v104, v138, v152
	v_add_u32_e32 v100, v104, v230
	ds_read_b128 v[92:95], v100
	v_add_u32_e32 v143, v104, v163
	ds_read_b128 v[104:107], v143 offset:64
	ds_read_b128 v[100:103], v100 offset:64
	ds_read_b128 v[108:111], v143 offset:2368
	v_cmp_ne_u32_e32 vcc, 0, v142
	s_waitcnt lgkmcnt(3)
	v_mfma_f32_16x16x32_bf16 v[96:99], v[92:95], v[0:3], 0
	ds_read_b128 v[144:147], v143 offset:4672
	v_mfma_f32_16x16x32_bf16 v[92:95], v[92:95], v[8:11], 0
	s_waitcnt lgkmcnt(2)
	v_mfma_f32_16x16x32_bf16 v[120:123], v[100:103], v[4:7], v[96:99]
	v_mfma_f32_16x16x32_bf16 v[100:103], v[100:103], v[12:15], v[92:95]
	s_nop 4
	ds_read_b128 v[92:95], v143
	s_waitcnt lgkmcnt(0)
	v_mfma_f32_16x16x32_bf16 v[96:99], v[92:95], v[0:3], 0
	v_mfma_f32_16x16x32_bf16 v[92:95], v[92:95], v[8:11], 0
	v_mfma_f32_16x16x32_bf16 v[116:119], v[104:107], v[4:7], v[96:99]
	v_mfma_f32_16x16x32_bf16 v[96:99], v[104:107], v[12:15], v[92:95]
	s_nop 5
	ds_read_b128 v[92:95], v143 offset:2304
	s_waitcnt lgkmcnt(0)
	v_mfma_f32_16x16x32_bf16 v[104:107], v[92:95], v[0:3], 0
	v_mfma_f32_16x16x32_bf16 v[112:115], v[108:111], v[4:7], v[104:107]
	s_nop 6
	ds_read_b128 v[104:107], v143 offset:4608
	v_mfma_f32_16x16x32_bf16 v[92:95], v[92:95], v[8:11], 0
	v_max3_f32 v143, v120, s49, v121
	v_max3_f32 v143, v143, v122, v123
	v_max3_f32 v143, v143, v116, v117
	v_mfma_f32_16x16x32_bf16 v[92:95], v[108:111], v[12:15], v[92:95]
	v_max3_f32 v143, v143, v118, v119
	v_max3_f32 v143, v143, v112, v113
	v_max3_f32 v143, v143, v114, v115
	s_waitcnt lgkmcnt(0)
	v_mfma_f32_16x16x32_bf16 v[108:111], v[104:107], v[0:3], 0
	v_mfma_f32_16x16x32_bf16 v[108:111], v[144:147], v[4:7], v[108:111]
	v_mfma_f32_16x16x32_bf16 v[104:107], v[104:107], v[8:11], 0
	v_mfma_f32_16x16x32_bf16 v[104:107], v[144:147], v[12:15], v[104:107]
	s_nop 5
	v_max3_f32 v143, v143, v108, v109
	v_max3_f32 v143, v143, v110, v111
	v_max3_f32 v144, v100, s49, v101
	v_max3_f32 v144, v144, v102, v103
	v_max3_f32 v144, v144, v96, v97
	v_max3_f32 v144, v144, v98, v99
	v_max3_f32 v144, v144, v92, v93
	v_max3_f32 v144, v144, v94, v95
	v_max3_f32 v144, v144, v104, v105
	v_max3_f32 v144, v144, v106, v107
	ds_bpermute_b32 v145, v225, v143
	ds_bpermute_b32 v146, v225, v144
	s_waitcnt lgkmcnt(1)
	v_max_f32_e32 v145, v145, v145
	v_max_f32_e32 v143, v143, v145
	s_waitcnt lgkmcnt(0)
	v_max_f32_e32 v146, v146, v146
	v_max_f32_e32 v144, v144, v146
	ds_bpermute_b32 v145, v224, v143
	ds_bpermute_b32 v146, v224, v144
	v_mov_b32_e32 v142, 0x7f61b1e6
	s_waitcnt lgkmcnt(1)
	v_max3_f32 v145, v141, v143, v145
	v_cndmask_b32_e32 v143, v141, v145, vcc
	v_cndmask_b32_e32 v142, v142, v143, vcc
	v_cmp_ne_u32_e32 vcc, 0, v140
	v_mov_b32_e32 v140, 0x7f61b1e6
	s_waitcnt lgkmcnt(0)
	v_max3_f32 v146, v139, v144, v146
	v_cndmask_b32_e32 v144, v139, v146, vcc
	s_nop 0
	v_cndmask_b32_e32 v140, v140, v144, vcc
	v_sub_f32_e32 v120, v120, v142
	v_sub_f32_e32 v121, v121, v142
	v_sub_f32_e32 v122, v122, v142
	v_sub_f32_e32 v123, v123, v142
	v_sub_f32_e32 v116, v116, v142
	v_sub_f32_e32 v117, v117, v142
	v_sub_f32_e32 v118, v118, v142
	v_sub_f32_e32 v119, v119, v142
	v_sub_f32_e32 v112, v112, v142
	v_sub_f32_e32 v113, v113, v142
	v_sub_f32_e32 v114, v114, v142
	v_sub_f32_e32 v115, v115, v142
	v_sub_f32_e32 v108, v108, v142
	v_sub_f32_e32 v109, v109, v142
	v_sub_f32_e32 v110, v110, v142
	v_sub_f32_e32 v111, v111, v142
	v_sub_f32_e32 v141, v141, v143
	v_sub_f32_e32 v100, v100, v140
	v_exp_f32_e32 v120, v120
	v_exp_f32_e32 v121, v121
	v_exp_f32_e32 v122, v122
	v_exp_f32_e32 v123, v123
	v_exp_f32_e32 v116, v116
	v_exp_f32_e32 v117, v117
	v_exp_f32_e32 v118, v118
	v_exp_f32_e32 v119, v119
	v_exp_f32_e32 v112, v112
	v_exp_f32_e32 v113, v113
	v_exp_f32_e32 v114, v114
	v_exp_f32_e32 v115, v115
	v_exp_f32_e32 v147, v108
	v_exp_f32_e32 v109, v109
	v_exp_f32_e32 v110, v110
	v_exp_f32_e32 v111, v111
	v_add_f32_e32 v145, 0, v120
	v_add_f32_e32 v145, v121, v145
	v_add_f32_e32 v145, v122, v145
	v_add_f32_e32 v145, v123, v145
	v_add_f32_e32 v145, v116, v145
	v_add_f32_e32 v145, v117, v145
	v_add_f32_e32 v145, v118, v145
	v_add_f32_e32 v145, v119, v145
	v_add_f32_e32 v145, v112, v145
	v_add_f32_e32 v145, v113, v145
	v_add_f32_e32 v145, v114, v145
	v_add_f32_e32 v145, v115, v145
	v_add_f32_e32 v108, v147, v145
	v_add_f32_e32 v108, v109, v108
	v_add_f32_e32 v108, v110, v108
	v_add_f32_e32 v145, v111, v108
	v_exp_f32_e32 v108, v141
	v_exp_f32_e32 v100, v100
	v_sub_f32_e32 v101, v101, v140
	v_exp_f32_e32 v101, v101
	v_sub_f32_e32 v102, v102, v140
	v_exp_f32_e32 v102, v102
	v_sub_f32_e32 v103, v103, v140
	v_exp_f32_e32 v103, v103
	v_sub_f32_e32 v96, v96, v140
	v_fmac_f32_e32 v145, v132, v108
	v_pk_mul_f32 v[90:91], v[90:91], v[108:109] op_sel_hi:[1,0]
	v_pk_mul_f32 v[88:89], v[88:89], v[108:109] op_sel_hi:[1,0]
	v_pk_mul_f32 v[86:87], v[86:87], v[108:109] op_sel_hi:[1,0]
	v_pk_mul_f32 v[84:85], v[84:85], v[108:109] op_sel_hi:[1,0]
	v_pk_mul_f32 v[82:83], v[82:83], v[108:109] op_sel_hi:[1,0]
	v_pk_mul_f32 v[80:81], v[80:81], v[108:109] op_sel_hi:[1,0]
	v_pk_mul_f32 v[78:79], v[78:79], v[108:109] op_sel_hi:[1,0]
	v_pk_mul_f32 v[76:77], v[76:77], v[108:109] op_sel_hi:[1,0]
	v_sub_f32_e32 v108, v139, v144
	v_add_f32_e32 v132, 0, v100
	v_exp_f32_e32 v139, v96
	v_add_f32_e32 v132, v101, v132
	v_add_f32_e32 v132, v102, v132
	v_add_f32_e32 v132, v103, v132
	v_sub_f32_e32 v97, v97, v140
	v_add_f32_e32 v96, v139, v132
	v_exp_f32_e32 v132, v97
	v_sub_f32_e32 v97, v98, v140
	v_exp_f32_e32 v141, v97
	v_sub_f32_e32 v97, v99, v140
	v_exp_f32_e32 v99, v97
	v_sub_f32_e32 v92, v92, v140
	v_exp_f32_e32 v142, v92
	v_sub_f32_e32 v93, v93, v140
	v_add_f32_e32 v96, v132, v96
	v_exp_f32_e32 v148, v93
	v_sub_f32_e32 v93, v94, v140
	v_add_f32_e32 v96, v141, v96
	v_exp_f32_e32 v149, v93
	v_sub_f32_e32 v93, v95, v140
	v_add_f32_e32 v96, v99, v96
	v_exp_f32_e32 v150, v93
	v_sub_f32_e32 v93, v104, v140
	v_add_f32_e32 v92, v142, v96
	v_exp_f32_e32 v104, v93
	v_sub_f32_e32 v93, v105, v140
	v_add_f32_e32 v92, v148, v92
	v_exp_f32_e32 v105, v93
	v_sub_f32_e32 v93, v106, v140
	v_add_f32_e32 v92, v149, v92
	v_exp_f32_e32 v106, v93
	v_sub_f32_e32 v93, v107, v140
	v_add_f32_e32 v92, v150, v92
	v_exp_f32_e32 v107, v93
	v_add_f32_e32 v92, v104, v92
	v_add_f32_e32 v92, v105, v92
	v_add_f32_e32 v92, v106, v92
	s_waitcnt lgkmcnt(0)
; template <bool BOUNDARY, bool Q0, bool Q1>
; __device__ __forceinline__ void attn_tile(const bf16* Ks, const bf16* Vt, const bf16x8 (&Qf)[2][2], const uint32_t (&vm)[2],
;                                           float (&m)[2], float (&l)[2], f32x4 (&O)[4][2], int fr, int fq) {
;     ...
;     l[qt] = l[qt] * alpha + ls;
; #pragma unroll
;     for (int dt = 0; dt < 4; ++dt) {
;       O[dt][qt][0] *= alpha; O[dt][qt][1] *= alpha; O[dt][qt][2] *= alpha; O[dt][qt][3] *= alpha;
;     }
;   }
; #pragma unroll
;   for (int kp = 0; kp < 2; ++kp) {
;     bf16x8 Pf[2];
; #pragma unroll
;     for (int qt = 0; qt < 2; ++qt) {
;       const u32x4 pk = {pack2(S[2 * kp][qt][0], S[2 * kp][qt][1]), pack2(S[2 * kp][qt][2], S[2 * kp][qt][3]),
;                         pack2(S[2 * kp + 1][qt][0], S[2 * kp + 1][qt][1]), pack2(S[2 * kp + 1][qt][2], S[2 * kp + 1][qt][3])};
;       Pf[qt] = __builtin_bit_cast(bf16x8, pk);
;     }
; #pragma unroll
;     for (int dt = 0; dt < 4; ++dt) {
;       const bf16x4 v0 = *(const bf16x4*)(Vt + (16 * dt + fr) * VT_LD + 32 * kp + 4 * fq);
;       const bf16x4 v1 = *(const bf16x4*)(Vt + (16 * dt + fr) * VT_LD + 32 * kp + 16 + 4 * fq);
;       bf16x8 vf;
;       vf[0] = v0[0]; vf[1] = v0[1]; vf[2] = v0[2]; vf[3] = v0[3];
;       vf[4] = v1[0]; vf[5] = v1[1]; vf[6] = v1[2]; vf[7] = v1[3];
;       if (Q0) O[dt][0] = __builtin_amdgcn_mfma_f32_16x16x32_bf16(vf, Pf[0], O[dt][0], 0, 0, 0);
;       if (Q1) O[dt][1] = __builtin_amdgcn_mfma_f32_16x16x32_bf16(vf, Pf[1], O[dt][1], 0, 0, 0);
;     }
;   }
	v_add_f32_e32 v146, v107, v92
	v_exp_f32_e32 v92, v108
	v_lshlrev_b32_e32 v108, 1, v223
	v_cvt_pk_bf16_f32 v96, v100, v101
	v_add3_u32 v100, v138, v231, v108
	v_fmac_f32_e32 v146, v133, v92
	v_pk_mul_f32 v[74:75], v[74:75], v[92:93] op_sel_hi:[1,0]
	v_pk_mul_f32 v[72:73], v[72:73], v[92:93] op_sel_hi:[1,0]
	v_pk_mul_f32 v[70:71], v[70:71], v[92:93] op_sel_hi:[1,0]
	v_pk_mul_f32 v[68:69], v[68:69], v[92:93] op_sel_hi:[1,0]
	v_pk_mul_f32 v[66:67], v[66:67], v[92:93] op_sel_hi:[1,0]
	v_pk_mul_f32 v[64:65], v[64:65], v[92:93] op_sel_hi:[1,0]
	v_pk_mul_f32 v[62:63], v[62:63], v[92:93] op_sel_hi:[1,0]
	v_pk_mul_f32 v[60:61], v[60:61], v[92:93] op_sel_hi:[1,0]
	v_cvt_pk_bf16_f32 v92, v120, v121
	v_add_u32_e32 v120, 0x2000, v100
	v_cvt_pk_bf16_f32 v97, v102, v103
	v_cvt_pk_bf16_f32 v93, v122, v123
	ds_read2_b64 v[100:103], v120 offset0:128 offset1:132
	v_cvt_pk_bf16_f32 v94, v116, v117
	v_cvt_pk_bf16_f32 v95, v118, v119
	v_cvt_pk_bf16_f32 v98, v139, v132
	v_cvt_pk_bf16_f32 v99, v141, v99
	v_lshlrev_b32_e32 v132, 1, v233
	v_add3_u32 v108, v138, v132, v108
	v_add_u32_e32 v121, 0x2000, v108
	v_add_u32_e32 v122, 0x2800, v108
	v_add_u32_e32 v123, 0x3000, v108
	v_cvt_pk_bf16_f32 v116, v112, v113
	v_cvt_pk_bf16_f32 v117, v114, v115
	ds_read2_b64 v[112:115], v122 offset0:144 offset1:148
	v_cvt_pk_bf16_f32 v118, v147, v109
	v_cvt_pk_bf16_f32 v119, v110, v111
	ds_read2_b64 v[108:111], v123 offset0:160 offset1:164
	v_cvt_pk_bf16_f32 v138, v142, v148
	v_cvt_pk_bf16_f32 v139, v149, v150
	v_cvt_pk_bf16_f32 v140, v104, v105
	v_cvt_pk_bf16_f32 v141, v106, v107
	ds_read2_b64 v[104:107], v121 offset0:128 offset1:132
	s_waitcnt lgkmcnt(3)
	v_mfma_f32_16x16x32_bf16 v[88:91], v[100:103], v[92:95], v[88:91]
	v_mfma_f32_16x16x32_bf16 v[72:75], v[100:103], v[96:99], v[72:75]
	ds_read2_b64 v[100:103], v120 offset0:136 offset1:140
	s_waitcnt lgkmcnt(3)
	v_mfma_f32_16x16x32_bf16 v[80:83], v[112:115], v[92:95], v[80:83]
	v_mfma_f32_16x16x32_bf16 v[64:67], v[112:115], v[96:99], v[64:67]
	ds_read2_b64 v[112:115], v122 offset0:152 offset1:156
	s_waitcnt lgkmcnt(3)
	v_mfma_f32_16x16x32_bf16 v[76:79], v[108:111], v[92:95], v[76:79]
	v_mfma_f32_16x16x32_bf16 v[60:63], v[108:111], v[96:99], v[60:63]
	ds_read2_b64 v[108:111], v121 offset0:136 offset1:140
	s_waitcnt lgkmcnt(3)
	v_mfma_f32_16x16x32_bf16 v[84:87], v[104:107], v[92:95], v[84:87]
	v_mfma_f32_16x16x32_bf16 v[68:71], v[104:107], v[96:99], v[68:71]
	ds_read2_b64 v[148:151], v123 offset0:168 offset1:172
	s_waitcnt lgkmcnt(3)
	v_mfma_f32_16x16x32_bf16 v[92:95], v[100:103], v[138:141], v[72:75]
	v_mfma_f32_16x16x32_bf16 v[100:103], v[100:103], v[116:119], v[88:91]
	s_waitcnt lgkmcnt(2)
	v_mfma_f32_16x16x32_bf16 v[104:107], v[112:115], v[138:141], v[64:67]
	v_mfma_f32_16x16x32_bf16 v[112:115], v[112:115], v[116:119], v[80:83]
	s_waitcnt lgkmcnt(1)
	v_mfma_f32_16x16x32_bf16 v[96:99], v[108:111], v[138:141], v[68:71]
	v_mfma_f32_16x16x32_bf16 v[108:111], v[108:111], v[116:119], v[84:87]
	s_waitcnt lgkmcnt(0)
	v_mfma_f32_16x16x32_bf16 v[120:123], v[148:151], v[116:119], v[76:79]
	v_mfma_f32_16x16x32_bf16 v[116:119], v[148:151], v[138:141], v[60:63]
